# DSA top-k score registers by batched LDS reads; branch GEMM tiles mapped so the 4 column tiles of a row block share an XCD
# speedup vs baseline: 1.0121x; 1.0121x over previous
;     __device__ bool next(int i, Unit& u) const { const int tile = c + (i >> 2) * G; if (tile >= ntile) return false; u.pm = tile >> 2; u.pn = (i & 3) * 4 + (tile & 3); return true; }
;     if (s == NSTEP - 1) { step_final(p); return; }
;     const int l = s / (NGRP * NK), g = (s / NK) % NGRP, k = s % NK;
;     if (k == 0) { if (g == 0) step_prep(p, l, lds); step_norm(p, l, g); }
;     else if (k == 1) { pg8::Gemm gm{p.hbuf, p.Wt, MG, NP, DM, 1 << 20, 0}; pg8::StaticOrder S; S.init(MG, NP, gridDim.x, blockIdx.x); EpiG1 E{p.proj, p.vT, p.kiP, p.gq}; pg8::gemm_phase(lds, gm, S, E); }
;     else if (k == 2) { step_mix(p, l, p.ctr + (l * NGRP + g) + 16 * rep, lds, rep ? REPT : 15, rep ? REPS : 63); }
;     else if (k == 3) { pg8::Gemm gm{p.ybuf, p.Wb, MG, 4096, 512, 4, (size_t)MG * 512 * 2}; pg8::BranchOrder S{(int)gridDim.x, (int)blockIdx.x, (MG / 256) * 4}; EpiG2 E{p.gq, p.hbuf}; pg8::gemm_phase(lds, gm, S, E); }
;     else { pg8::Gemm gm{p.hbuf, p.Wo, MG, DM, DM, 1 << 20, 0}; pg8::StaticOrder S; S.init(MG, DM, gridDim.x, blockIdx.x); EpiG3 E{(l == 0) ? p.x : p.out, rep ? (float*)p.proj - (size_t)g * MG * DM : p.out, g * MG}; pg8::gemm_phase(lds, gm, S, E); }
; }
.LBB0_5:
	s_or_b64 exec, exec, s[2:3]
	s_load_dwordx2 s[2:3], s[0:1], 0xe0
	s_waitcnt lgkmcnt(0)
	v_writelane_b32 v251, s2, 15
	s_nop 1
	v_writelane_b32 v251, s3, 16
	s_cmp_ge_i32 s2, s3
	s_cbranch_scc1 .LBB0_1264
	v_readlane_b32 s26, v251, 0
	s_cmpk_lt_i32 s26, 0x100
	s_cselect_b64 s[2:3], -1, 0
	s_load_dwordx16 s[44:59], s[0:1], 0x0
	s_load_dwordx16 s[4:19], s[0:1], 0x80
	v_writelane_b32 v251, s2, 17
	s_and_b32 s22, s26, 7
	s_lshl_b32 s22, s22, 5
	s_lshr_b32 s21, s26, 3
	s_add_i32 s21, s22, s21
	s_ashr_i32 s22, s21, 2
	s_and_b32 s21, s21, 3
	v_writelane_b32 v251, s3, 18
	s_mov_b32 s2, s22
	v_writelane_b32 v251, s2, 19
	s_ashr_i32 s23, s22, 31
	s_load_dwordx2 s[28:29], s[0:1], 0xe8
	v_writelane_b32 v251, s3, 20
	s_lshl_b64 s[2:3], s[22:23], 18
	v_writelane_b32 v251, s21, 21
	s_lshl_b32 s21, s21, 18
	s_waitcnt lgkmcnt(0)
	s_add_u32 s22, s6, s21
	s_addc_u32 s23, s7, 0
	s_add_u32 s2, s16, s2
	s_addc_u32 s3, s17, s3
	s_add_u32 s24, s22, 0x20000
	s_addc_u32 s25, s23, 0
	v_writelane_b32 v251, s24, 22
	s_load_dwordx8 s[36:43], s[0:1], 0xc0
	v_lshrrev_b32_e32 v1, 20, v0
	v_writelane_b32 v251, s25, 23
	s_add_u32 s24, s2, 0x20000
	v_writelane_b32 v251, s2, 24
	s_addc_u32 s25, s3, 0
	v_lshrrev_b32_e32 v0, 10, v0
	v_writelane_b32 v251, s3, 25
	v_writelane_b32 v251, s24, 26
	s_add_u32 s2, s22, 0x20080
	v_or_b32_e32 v0, v0, v1
	v_writelane_b32 v251, s25, 27
	v_writelane_b32 v251, s22, 28
	s_addc_u32 s3, s23, 0
	s_cmpk_lt_i32 s26, 0xb00
	v_writelane_b32 v251, s23, 29
	v_writelane_b32 v251, s2, 30
	s_movk_i32 s22, 0x161
	s_mov_b64 s[66:67], s[58:59]
	v_writelane_b32 v251, s3, 31
	s_cselect_b64 s[2:3], -1, 0
	v_writelane_b32 v251, s2, 32
	s_mov_b64 s[64:65], s[56:57]
	v_mbcnt_lo_u32_b32 v205, -1, 0
	v_writelane_b32 v251, s3, 33
	s_ashr_i32 s2, s26, 31
	v_writelane_b32 v251, s2, 34
	s_lshr_b32 s2, s2, 29
	s_add_i32 s2, s26, s2
	s_ashr_i32 s3, s2, 3
	s_and_b32 s2, s2, -8
	s_sub_i32 s2, s26, s2
	s_lshl_b32 s21, s2, 5
	s_cmp_lt_i32 s2, 0
	s_cselect_b32 s22, s22, 0x160
	s_mul_i32 s22, s22, s2
	s_mul_i32 s23, s2, 33
	s_cselect_b32 s24, s23, s21
	s_add_i32 s22, s22, s3
	s_mul_hi_i32 s21, s22, 0x2e8ba2e9
	s_lshr_b32 s23, s21, 31
	s_ashr_i32 s21, s21, 5
	s_add_i32 s21, s21, s23
	s_mul_i32 s23, s21, 0xb0
	s_sub_i32 s22, s22, s23
	s_bfe_u32 s23, s22, 0x2001d
	s_add_i32 s23, s22, s23
	s_sext_i32_i16 s25, s23
	s_and_b32 s23, s23, 0xfffc
	s_ashr_i32 s25, s25, 2
	s_sub_i32 s22, s22, s23
	s_mul_i32 s2, s2, 5
	s_lshl_b32 s21, s21, 2
	s_sext_i32_i16 s22, s22
	s_add_i32 s2, s2, s25
	s_add_i32 s30, s21, s22
	s_bfe_i32 s21, s2, 0x80000
	s_mul_i32 s21, s21, 47
	s_sext_i32_i16 s22, s21
	s_ashr_i32 s22, s22, 11
	s_bfe_u32 s21, s21, 0x1000f
	s_add_i32 s21, s22, s21
	s_mul_i32 s21, s21, 44
	s_sub_i32 s2, s2, s21
	s_ashr_i32 s21, s28, 31
	s_cmpk_lt_i32 s26, 0xf10
	v_writelane_b32 v251, s21, 35
	s_cselect_b64 s[22:23], -1, 0
	v_writelane_b32 v251, s22, 36
	s_cmp_lg_u64 s[58:59], 0
	v_mov_b32_e32 v1, 0
	v_writelane_b32 v251, s23, 37
	s_cselect_b64 s[22:23], -1, 0
	v_writelane_b32 v251, s22, 38
	s_lshl_b32 s21, s26, 3
	s_lshl_b32 s82, s28, 3
	v_writelane_b32 v251, s23, 39
	s_load_dwordx2 s[22:23], s[0:1], 0xe0
	v_writelane_b32 v251, s21, 40
	v_mov_b32_e32 v199, 0x358637bd
	v_mov_b32_e32 v200, 0x10001
	v_mov_b32_e32 v201, 0x3ecc95a3
	s_waitcnt lgkmcnt(0)
	s_cmp_gt_i32 s23, -1
	s_cselect_b64 s[22:23], -1, 0
	v_writelane_b32 v251, s22, 41
	v_mov_b32_e32 v202, 1
	v_mov_b32_e32 v203, 0x3b808081
	v_writelane_b32 v251, s23, 42
	s_add_u32 s22, s40, 0x200
	s_addc_u32 s23, s41, 0
	v_writelane_b32 v251, s22, 43
	v_mov_b32_e32 v204, 0xa00
	v_mbcnt_hi_u32_b32 v206, -1, v205
	v_writelane_b32 v251, s23, 44
	s_add_u32 s22, s40, 0x1000
	s_addc_u32 s23, s41, 0
	v_writelane_b32 v251, s22, 45
	v_mov_b32_e32 v207, 0xfff0fff
	v_mov_b32_e32 v208, 0xff800000
	v_writelane_b32 v251, s23, 46
	s_add_u32 s22, s40, 0x1100
	s_addc_u32 s23, s41, 0
	v_writelane_b32 v251, s22, 47
	v_mov_b32_e32 v162, 0x3f317218
	v_mov_b32_e32 v209, 0x7f800000
	v_writelane_b32 v251, s23, 48
	s_add_u32 s22, s40, 0x1200
	s_addc_u32 s23, s41, 0
	v_writelane_b32 v251, s22, 49
	v_mov_b32_e32 v210, 0x7fc00000
	v_mov_b64_e32 v[164:165], 0xaff
	v_writelane_b32 v251, s23, 50
	s_add_u32 s22, s40, 0x1300
	s_addc_u32 s23, s41, 0
	v_writelane_b32 v251, s22, 51
	s_cmp_eq_u32 s20, 15
	v_mov_b64_e32 v[166:167], 0xb00
	v_writelane_b32 v251, s23, 52
	s_cselect_b64 s[22:23], -1, 0
	v_writelane_b32 v251, s22, 53
	s_cmp_eq_u32 s20, 14
	v_mov_b64_e32 v[168:169], 0xff
	v_writelane_b32 v251, s23, 54
	s_cselect_b64 s[22:23], -1, 0
	v_writelane_b32 v251, s22, 55
	s_cmp_eq_u32 s20, 13
	v_mov_b64_e32 v[170:171], 0x100
	v_writelane_b32 v251, s23, 56
	s_cselect_b64 s[22:23], -1, 0
	v_writelane_b32 v251, s22, 57
	s_cmp_eq_u32 s20, 12
	s_movk_i32 s84, 0x2000
	v_writelane_b32 v251, s23, 58
	s_cselect_b64 s[22:23], -1, 0
	v_writelane_b32 v251, s22, 59
	s_cmp_eq_u32 s20, 11
	s_movk_i32 s33, 0x5800
	v_writelane_b32 v251, s23, 60
	s_cselect_b64 s[22:23], -1, 0
	v_writelane_b32 v251, s22, 61
	s_cmp_eq_u32 s20, 10
	s_mov_b32 s85, 0x800000
	v_writelane_b32 v251, s23, 62
	s_cselect_b64 s[22:23], -1, 0
	v_writelane_b32 v251, s22, 63
	s_cmp_eq_u32 s20, 9
	s_mov_b32 s86, 0xd000
	v_writelane_b32 v252, s23, 0
	s_cselect_b64 s[22:23], -1, 0
	v_writelane_b32 v252, s22, 1
	s_cmp_eq_u32 s20, 8
	s_movk_i32 s87, 0x204
	v_writelane_b32 v252, s23, 2
	s_cselect_b64 s[22:23], -1, 0
	v_writelane_b32 v252, s22, 3
	s_cmp_eq_u32 s20, 7
	s_mov_b64 s[90:91], 0x800
	v_writelane_b32 v252, s23, 4
	s_cselect_b64 s[22:23], -1, 0
	v_writelane_b32 v252, s22, 5
	s_cmp_eq_u32 s20, 6
	s_nop 0
	v_writelane_b32 v252, s23, 6
	s_cselect_b64 s[22:23], -1, 0
	v_writelane_b32 v252, s22, 7
	s_cmp_eq_u32 s20, 5
; #define LAS __attribute__((address_space(3)))
;     if (s == NSTEP - 1) { step_final(p); return; }
;     const int l = s / (NGRP * NK), g = (s / NK) % NGRP, k = s % NK;
;     if (k == 0) { if (g == 0) step_prep(p, l, lds); step_norm(p, l, g); }
;     else if (k == 1) { pg8::Gemm gm{p.hbuf, p.Wt, MG, NP, DM, 1 << 20, 0}; pg8::StaticOrder S; S.init(MG, NP, gridDim.x, blockIdx.x); EpiG1 E{p.proj, p.vT, p.kiP, p.gq}; pg8::gemm_phase(lds, gm, S, E); }
;     else if (k == 2) { step_mix(p, l, p.ctr + (l * NGRP + g) + 16 * rep, lds, rep ? REPT : 15, rep ? REPS : 63); }
;     else if (k == 3) { pg8::Gemm gm{p.ybuf, p.Wb, MG, 4096, 512, 4, (size_t)MG * 512 * 2}; pg8::BranchOrder S{(int)gridDim.x, (int)blockIdx.x, (MG / 256) * 4}; EpiG2 E{p.gq, p.hbuf}; pg8::gemm_phase(lds, gm, S, E); }
;     else { pg8::Gemm gm{p.hbuf, p.Wo, MG, DM, DM, 1 << 20, 0}; pg8::StaticOrder S; S.init(MG, DM, gridDim.x, blockIdx.x); EpiG3 E{(l == 0) ? p.x : p.out, rep ? (float*)p.proj - (size_t)g * MG * DM : p.out, g * MG}; pg8::gemm_phase(lds, gm, S, E); }
; }
; __global__ __launch_bounds__(512, 2) void mega(Params p, int s0, int s1) {
;     extern __shared__ __attribute__((aligned(16))) unsigned char shm[];
;     LAS unsigned char* lds = (LAS unsigned char*)shm;
;     cg::grid_group grid = cg::this_grid();
;     volatile LAS unsigned* st = (volatile LAS unsigned*)(lds + XB_ST_OFF);
;     if (threadIdx.x == 0) { st[0] = 0u; st[1] = 0u; }
;     __syncthreads();
;     const XcdBarrier xb = xcd_barrier_post(p.bar, st);
;     for (int s = s0; s < s1; ++s) { run_step(p, s, lds);
;         if (s + 1 < s1) { if (s1 < 0) grid.sync(); else xcd_barrier(xb); } }
; }
	s_nop 0
	v_writelane_b32 v252, s23, 8
	s_cselect_b64 s[22:23], -1, 0
	v_writelane_b32 v252, s22, 9
	s_cmp_eq_u32 s20, 4
	s_nop 0
	v_writelane_b32 v252, s23, 10
	s_cselect_b64 s[22:23], -1, 0
	v_writelane_b32 v252, s22, 11
	s_cmp_eq_u32 s20, 3
	s_nop 0
	v_writelane_b32 v252, s23, 12
	s_cselect_b64 s[22:23], -1, 0
	v_writelane_b32 v252, s22, 13
	s_cmp_eq_u32 s20, 2
	s_nop 0
	v_writelane_b32 v252, s23, 14
	s_cselect_b64 s[22:23], -1, 0
	v_writelane_b32 v252, s22, 15
	s_cmp_eq_u32 s20, 1
	s_nop 0
	v_writelane_b32 v252, s23, 16
	s_cselect_b64 s[22:23], -1, 0
	v_writelane_b32 v252, s22, 17
	s_cmp_eq_u32 s20, 0
	s_nop 0
	v_writelane_b32 v252, s23, 18
	s_cselect_b64 s[22:23], -1, 0
	s_lshl_b32 s20, s20, 8
	s_add_u32 s20, s40, s20
	v_writelane_b32 v252, s22, 19
	s_addc_u32 s21, s41, 0
	s_nop 0
	v_writelane_b32 v252, s23, 20
	s_add_u32 s22, s20, 0x1400
	s_addc_u32 s23, s21, 0
	v_writelane_b32 v252, s22, 21
	s_add_u32 s20, s20, 0x2400
	s_addc_u32 s21, s21, 0
	v_writelane_b32 v252, s23, 22
	v_writelane_b32 v252, s20, 23
	s_mov_b32 s22, s30
	s_nop 0
	v_writelane_b32 v252, s21, 24
	s_add_u32 s20, s40, 0x3400
	s_addc_u32 s21, s41, 0
	v_writelane_b32 v252, s20, 25
	s_nop 1
	v_writelane_b32 v252, s21, 26
	s_add_u32 s20, s40, 0x3500
	s_addc_u32 s21, s41, 0
	v_writelane_b32 v252, s20, 27
	s_ashr_i32 s31, s30, 31
	s_nop 0
	v_writelane_b32 v252, s21, 28
	s_bfe_i64 s[20:21], s[2:3], 0x80000
	v_writelane_b32 v252, s22, 29
	s_lshl_b64 s[20:21], s[20:21], 19
	s_sext_i32_i8 s2, s2
	v_writelane_b32 v252, s23, 30
	s_lshl_b64 s[22:23], s[30:31], 19
	s_add_u32 s20, s4, s20
	s_addc_u32 s21, s5, s21
	s_add_u32 s22, s12, s22
	s_addc_u32 s23, s13, s23
	s_add_u32 s30, s20, 0x40000
	s_addc_u32 s31, s21, 0
	v_writelane_b32 v252, s30, 31
	s_nop 1
	v_writelane_b32 v252, s31, 32
	s_add_u32 s30, s22, 0x40000
	v_writelane_b32 v252, s22, 33
	s_addc_u32 s31, s23, 0
	s_nop 0
	v_writelane_b32 v252, s23, 34
	v_writelane_b32 v252, s30, 35
	s_add_u32 s22, s20, 0x40080
	s_nop 0
	v_writelane_b32 v252, s31, 36
	v_writelane_b32 v252, s20, 37
	s_addc_u32 s23, s21, 0
	s_add_i32 s3, s24, s3
	v_writelane_b32 v252, s21, 38
	s_ashr_i32 s20, s3, 31
	s_lshr_b32 s20, s20, 28
	s_add_i32 s20, s3, s20
	s_and_b32 s21, s20, 0xfff0
	s_sub_i32 s3, s3, s21
	s_bfe_i32 s21, s3, 0x80000
	s_bfe_u32 s21, s21, 0x2000d
	v_writelane_b32 v252, s22, 39
	s_add_i32 s21, s3, s21
	s_ashr_i32 s20, s20, 4
	v_writelane_b32 v252, s23, 40
	s_and_b32 s22, s21, 0xfc
	s_sub_i32 s3, s3, s22
	s_bfe_i32 s21, s21, 0x80000
	s_lshl_b32 s20, s20, 2
	s_sext_i32_i16 s21, s21
	s_sext_i32_i8 s3, s3
	s_add_i32 s24, s20, s3
	s_ashr_i32 s3, s21, 2
	v_writelane_b32 v252, s3, 41
	s_lshr_b32 s20, s21, 2
	s_mov_b32 s22, s24
	s_load_dword s3, s[0:1], 0xf0
	s_ashr_i32 s25, s24, 31
	s_bfe_i64 s[20:21], s[20:21], 0x100000
	v_writelane_b32 v252, s22, 42
	s_lshl_b64 s[20:21], s[20:21], 19
	s_mov_b32 s31, 0
	v_writelane_b32 v252, s23, 43
	s_lshl_b64 s[22:23], s[24:25], 19
	s_add_u32 s20, s8, s20
	s_addc_u32 s21, s9, s21
	v_writelane_b32 v252, s2, 44
	s_mul_i32 s2, s29, s28
	s_add_u32 s22, s12, s22
	s_waitcnt lgkmcnt(0)
	s_mul_i32 s2, s2, s3
	s_addc_u32 s23, s13, s23
	v_writelane_b32 v252, s2, 45
	s_movk_i32 s2, 0x3ff
	v_and_or_b32 v0, v0, s2, v198
	s_add_u32 s2, s20, 0x40000
	s_addc_u32 s3, s21, 0
	v_writelane_b32 v252, s2, 46
	s_nop 1
	v_writelane_b32 v252, s3, 47
	s_add_u32 s2, s22, 0x40000
	v_writelane_b32 v252, s22, 48
	s_addc_u32 s3, s23, 0
	s_nop 0
	v_writelane_b32 v252, s23, 49
	v_writelane_b32 v252, s2, 50
	s_nop 1
	v_writelane_b32 v252, s3, 51
	s_add_u32 s2, s20, 0x40080
	v_writelane_b32 v252, s20, 52
	s_addc_u32 s3, s21, 0
	s_nop 0
	v_writelane_b32 v252, s21, 53
	v_writelane_b32 v252, s2, 54
	s_nop 1
	v_writelane_b32 v252, s3, 55
	s_add_u32 s2, s54, 64
	s_addc_u32 s3, s55, 0
	v_writelane_b32 v252, s2, 56
	s_mov_b64 s[60:61], s[52:53]
	s_mov_b64 s[58:59], s[50:51]
	v_writelane_b32 v252, s3, 57
	s_add_u32 s2, s48, 0x1810
	v_writelane_b32 v252, s2, 58
	s_addc_u32 s2, s49, 0
	v_writelane_b32 v252, s2, 59
	s_lshl_b32 s2, s26, 2
	v_writelane_b32 v252, s2, 60
	s_lshl_b32 s2, s28, 2
	v_writelane_b32 v252, s2, 61
	s_add_u32 s2, s48, 0xc730
	v_writelane_b32 v252, s2, 62
	s_addc_u32 s2, s49, 0
	v_writelane_b32 v252, s2, 63
	s_add_u32 s2, s48, 0x17650
	v_writelane_b32 v253, s2, 0
	s_addc_u32 s2, s49, 0
	v_writelane_b32 v253, s2, 1
	s_add_u32 s2, s48, 0x22570
	v_writelane_b32 v253, s2, 2
	s_mov_b64 s[56:57], s[48:49]
	s_mov_b64 s[54:55], s[46:47]
	s_mov_b64 s[52:53], s[44:45]
	v_writelane_b32 v253, s52, 3
	s_addc_u32 s2, s49, 0
	s_load_dwordx16 s[36:51], s[0:1], 0x40
	v_writelane_b32 v253, s53, 4
	v_writelane_b32 v253, s54, 5
	v_writelane_b32 v253, s55, 6
	v_writelane_b32 v253, s56, 7
	v_writelane_b32 v253, s57, 8
	v_writelane_b32 v253, s58, 9
	v_writelane_b32 v253, s59, 10
	v_writelane_b32 v253, s60, 11
	v_writelane_b32 v253, s61, 12
	v_writelane_b32 v253, s62, 13
	v_writelane_b32 v253, s63, 14
	v_writelane_b32 v253, s64, 15
	v_writelane_b32 v253, s65, 16
	v_writelane_b32 v253, s66, 17
	v_writelane_b32 v253, s67, 18
	v_writelane_b32 v253, s2, 19
	s_add_u32 s2, s12, 0x400
	s_addc_u32 s3, s13, 0
	v_writelane_b32 v253, s2, 20
	s_waitcnt lgkmcnt(0)
	s_add_u32 s0, s50, 0xc00
	v_writelane_b32 v253, s3, 21
	v_writelane_b32 v253, s36, 22
	s_addc_u32 s1, s51, 0
	s_ashr_i32 s83, s82, 31
	v_writelane_b32 v253, s37, 23
	v_writelane_b32 v253, s38, 24
	v_writelane_b32 v253, s39, 25
	v_writelane_b32 v253, s40, 26
	v_writelane_b32 v253, s41, 27
	v_writelane_b32 v253, s42, 28
	v_writelane_b32 v253, s43, 29
	v_writelane_b32 v253, s44, 30
	v_writelane_b32 v253, s45, 31
	v_writelane_b32 v253, s46, 32
	v_writelane_b32 v253, s47, 33
	v_writelane_b32 v253, s48, 34
	v_writelane_b32 v253, s49, 35
	v_writelane_b32 v253, s50, 36
	v_writelane_b32 v253, s51, 37
	v_writelane_b32 v253, s0, 38
	s_lshl_b64 s[88:89], s[82:83], 12
	s_mov_b64 s[2:3], 0x80
	v_writelane_b32 v253, s1, 39
	s_add_i32 s0, 0, 0x202c0
	v_writelane_b32 v253, s0, 40
	s_add_i32 s0, 0, 0x24000
	v_writelane_b32 v253, s0, 41
	s_add_i32 s0, 0, 0x24004
	v_writelane_b32 v253, s0, 42
	v_cmp_eq_u32_e64 s[0:1], 0, v0
	s_mov_b32 s36, 0x3e0293ee
	s_nop 0
	v_writelane_b32 v253, s0, 43
	s_nop 1
	v_writelane_b32 v253, s1, 44
	s_mov_b32 s0, s82
	v_writelane_b32 v253, s0, 45
	s_nop 1
	v_writelane_b32 v253, s1, 46
	v_writelane_b32 v253, s88, 47
	s_nop 1
	v_writelane_b32 v253, s89, 48
	s_branch .LBB0_11

;     __device__ bool next(int i, Unit& u) const { const int tile = c + (i >> 2) * G; if (tile >= ntile) return false; u.pm = tile >> 2; u.pn = (i & 3) * 4 + (tile & 3); return true; }
; template <class Epi, class Sched>
; __device__ __forceinline__ void gemm_phase(LAS unsigned char* lds, const Gemm g, const Sched& S, const Epi& E) {
;     ...
;     for (;;) {
;         const bool has_next = S.next(ui + 1, nxt);
;         const char* nA = has_next ? (const char*)g.A + (size_t)nxt.pm * tstep + (size_t)(nxt.pn / g.pn_per_grp) * g.a_grp_bytes : cA; const char* nB = has_next ? (const char*)g.Bt + (size_t)nxt.pn * tstep : cB;
.LBB0_22:
	s_add_i32 s52, s52, 1
	s_mov_b32 s30, s0
	s_lshr_b32 s0, s52, 2
	v_readlane_b32 s24, v251, 9
	s_mul_i32 s0, s0, s24
	v_readlane_b32 s24, v251, 0
	s_nop 0
	s_and_b32 s25, s24, 7
	s_lshl_b32 s25, s25, 5
	s_lshr_b32 s24, s24, 3
	s_add_i32 s24, s24, s25
	s_add_i32 s0, s0, s24
	s_cmpk_lt_i32 s0, 0x100
	s_cselect_b64 s[34:35], -1, 0
	s_lshl_b32 s24, s52, 2
	s_and_b32 s37, s24, 12
	s_and_b32 s24, s0, 3
	s_mov_b32 s1, s53
	s_mov_b32 s54, s53
	v_readlane_b32 s25, v251, 10
	s_or_b32 s53, s24, s37
	s_ashr_i32 s0, s0, 2
	s_and_b64 s[24:25], s[34:35], exec
	s_cselect_b32 s24, s53, s1
	s_ashr_i32 s1, s0, 31
	s_lshl_b64 s[38:39], s[0:1], 18
	s_add_u32 s1, s16, s38
	s_addc_u32 s25, s17, s39
	s_lshl_b32 s37, s37, 22
	s_mov_b64 s[20:21], s[46:47]
	s_add_u32 s46, s1, s37
	s_addc_u32 s47, s25, 0
	s_and_b64 s[38:39], s[34:35], exec
	s_cselect_b32 s1, s47, s21
	s_cselect_b32 s37, s46, s20
	s_ashr_i32 s25, s24, 31
	s_lshl_b64 s[24:25], s[24:25], 18
	s_mov_b64 s[22:23], s[48:49]
	s_add_u32 s48, s6, s24
	s_addc_u32 s49, s7, s25
	s_and_b64 s[24:25], s[34:35], exec
	s_cselect_b32 s38, s49, s23
	s_cselect_b32 s39, s48, s22
	s_add_u32 s20, s20, 0x20080
	s_addc_u32 s21, s21, 0
	s_add_u32 s40, s22, 0x100
	s_addc_u32 s41, s23, 0
	s_mov_b32 s42, -2

; #define LAS __attribute__((address_space(3)))
; __device__ __forceinline__ unsigned sortable(float f) { const unsigned b = __float_as_uint(f); return (b & 0x80000000u) ? ~b : (b | 0x80000000u); }
;     ...
;     { unsigned u[64];
;       LAS float* srow = sc + wid * 4096;
; #pragma unroll
;       for (int r = 0; r < 64; ++r) { u[r] = 0u; if (r * 64 < n) { const float f = srow[r * 64 + lane]; u[r] = (r * 64 + lane < n) ? sortable(f) : 0u; } }
;       const int nreg = (n + 63) >> 6;
.LBB0_198:
	s_add_i32 s61, s64, s30
	s_lshl_b32 s0, s64, 14
	s_add_i32 s60, s0, 0
	v_cmp_lt_i32_e64 s[0:1], s61, v163
	v_cmp_ge_i32_e32 vcc, s61, v163
	v_mov_b32_e32 v5, 0
	v_writelane_b32 v254, s0, 0
	v_mov_b32_e32 v6, 0
	s_waitcnt lgkmcnt(0)
	v_writelane_b32 v254, s1, 1
	s_barrier
	s_cmp_gt_i32 s61, 63
	s_cselect_b64 s[0:1], -1, 0
	v_writelane_b32 v254, s0, 2
	s_nop 1
	v_writelane_b32 v254, s1, 3
	s_cmpk_gt_i32 s61, 0x7f
	s_cselect_b64 s[0:1], -1, 0
	v_writelane_b32 v254, s0, 4
	s_nop 1
	v_writelane_b32 v254, s1, 5
	s_cmpk_gt_i32 s61, 0xbf
	s_cselect_b64 s[0:1], -1, 0
	v_writelane_b32 v254, s0, 6
	s_nop 1
	v_writelane_b32 v254, s1, 7
	s_cmpk_gt_i32 s61, 0xff
	s_cselect_b64 s[0:1], -1, 0
	v_writelane_b32 v254, s0, 8
	s_nop 1
	v_writelane_b32 v254, s1, 9
	s_cmpk_gt_i32 s61, 0x13f
	s_cselect_b64 s[0:1], -1, 0
	v_writelane_b32 v254, s0, 10
	s_nop 1
	v_writelane_b32 v254, s1, 11
	s_cmpk_gt_i32 s61, 0x17f
	s_cselect_b64 s[0:1], -1, 0
	v_writelane_b32 v254, s0, 12
	s_nop 1
	v_writelane_b32 v254, s1, 13
	s_cmpk_gt_i32 s61, 0x1bf
	s_cselect_b64 s[0:1], -1, 0
	v_writelane_b32 v254, s0, 14
	s_nop 1
	v_writelane_b32 v254, s1, 15
	s_cmpk_gt_i32 s61, 0x1ff
	s_cselect_b64 s[0:1], -1, 0
	v_writelane_b32 v254, s0, 16
	s_nop 1
	v_writelane_b32 v254, s1, 17
	s_cmpk_gt_i32 s61, 0x23f
	s_cselect_b64 s[0:1], -1, 0
	v_writelane_b32 v254, s0, 18
	s_nop 1
	v_writelane_b32 v254, s1, 19
	s_cmpk_gt_i32 s61, 0x27f
	s_cselect_b64 s[0:1], -1, 0
	v_writelane_b32 v254, s0, 20
	s_nop 1
	v_writelane_b32 v254, s1, 21
	s_cmpk_gt_i32 s61, 0x2bf
	s_cselect_b64 s[0:1], -1, 0
	v_writelane_b32 v254, s0, 22
	s_nop 1
	v_writelane_b32 v254, s1, 23
	s_cmpk_gt_i32 s61, 0x2ff
	s_cselect_b64 s[0:1], -1, 0
	v_writelane_b32 v254, s0, 24
	s_nop 1
	v_writelane_b32 v254, s1, 25
	s_cmpk_gt_i32 s61, 0x33f
	s_cselect_b64 s[0:1], -1, 0
	v_writelane_b32 v254, s0, 26
	s_nop 1
	v_writelane_b32 v254, s1, 27
	s_cmpk_gt_i32 s61, 0x37f
	s_cselect_b64 s[0:1], -1, 0
	v_writelane_b32 v254, s0, 28
	s_nop 1
	v_writelane_b32 v254, s1, 29
	s_cmpk_gt_i32 s61, 0x3bf
	s_cselect_b64 s[0:1], -1, 0
	v_writelane_b32 v254, s0, 30
	s_nop 1
	v_writelane_b32 v254, s1, 31
	s_cmpk_gt_i32 s61, 0x3ff
	s_cselect_b64 s[0:1], -1, 0
	v_writelane_b32 v254, s0, 32
	s_nop 1
	v_writelane_b32 v254, s1, 33
	s_cmpk_gt_i32 s61, 0x43f
	s_cselect_b64 s[0:1], -1, 0
	v_writelane_b32 v254, s0, 34
	s_nop 1
	v_writelane_b32 v254, s1, 35
	s_cmpk_gt_i32 s61, 0x47f
	s_cselect_b64 s[0:1], -1, 0
	v_writelane_b32 v254, s0, 36
	s_nop 1
	v_writelane_b32 v254, s1, 37
	s_cmpk_gt_i32 s61, 0x4bf
	s_cselect_b64 s[0:1], -1, 0
	v_writelane_b32 v254, s0, 38
	s_nop 1
	v_writelane_b32 v254, s1, 39
	s_cmpk_gt_i32 s61, 0x4ff
	s_cselect_b64 s[0:1], -1, 0
	v_writelane_b32 v254, s0, 40
	s_nop 1
	v_writelane_b32 v254, s1, 41
	s_cmpk_gt_i32 s61, 0x53f
	s_cselect_b64 s[0:1], -1, 0
	v_writelane_b32 v254, s0, 42
	s_nop 1
	v_writelane_b32 v254, s1, 43
	s_cmpk_gt_i32 s61, 0x57f
	s_cselect_b64 s[0:1], -1, 0
	v_writelane_b32 v254, s0, 44
	s_nop 1
	v_writelane_b32 v254, s1, 45
	s_cmpk_gt_i32 s61, 0x5bf
	s_cselect_b64 s[0:1], -1, 0
	v_writelane_b32 v254, s0, 46
	s_nop 1
	v_writelane_b32 v254, s1, 47
	s_cmpk_gt_i32 s61, 0x5ff
	s_cselect_b64 s[0:1], -1, 0
	v_writelane_b32 v254, s0, 48
	s_nop 1
	v_writelane_b32 v254, s1, 49
	s_cmpk_gt_i32 s61, 0x63f
	s_cselect_b64 s[0:1], -1, 0
	v_writelane_b32 v254, s0, 50
	s_nop 1
	v_writelane_b32 v254, s1, 51
	s_cmpk_gt_i32 s61, 0x67f
	s_cselect_b64 s[0:1], -1, 0
	v_writelane_b32 v254, s0, 52
	s_nop 1
	v_writelane_b32 v254, s1, 53
	s_cmpk_gt_i32 s61, 0x6bf
	s_cselect_b64 s[0:1], -1, 0
	v_writelane_b32 v254, s0, 54
	s_nop 1
	v_writelane_b32 v254, s1, 55
	s_cmpk_gt_i32 s61, 0x6ff
	s_cselect_b64 s[0:1], -1, 0
	v_writelane_b32 v254, s0, 56
	s_nop 1
	v_writelane_b32 v254, s1, 57
	s_cmpk_gt_i32 s61, 0x73f
	s_cselect_b64 s[0:1], -1, 0
	v_writelane_b32 v254, s0, 58
	s_nop 1
	v_writelane_b32 v254, s1, 59
	s_cmpk_gt_i32 s61, 0x77f
	s_cselect_b64 s[0:1], -1, 0
	v_writelane_b32 v254, s0, 60
	s_nop 1
	v_writelane_b32 v254, s1, 61
	s_cmpk_gt_i32 s61, 0x7bf
	s_cselect_b64 s[0:1], -1, 0
	v_writelane_b32 v254, s0, 62
	s_nop 1
	v_writelane_b32 v254, s1, 63
	s_cmpk_gt_i32 s61, 0x7ff
	s_cselect_b64 s[0:1], -1, 0
	v_writelane_b32 v250, s0, 0
	s_nop 1
	v_writelane_b32 v250, s1, 1
	s_cmpk_gt_i32 s61, 0x83f
	s_cselect_b64 s[0:1], -1, 0
	v_writelane_b32 v250, s0, 2
	s_nop 1
	v_writelane_b32 v250, s1, 3
	s_cmpk_gt_i32 s61, 0x87f
	s_cselect_b64 s[0:1], -1, 0
	v_writelane_b32 v250, s0, 4
	s_nop 1
	v_writelane_b32 v250, s1, 5
	s_cmpk_gt_i32 s61, 0x8bf
	s_cselect_b64 s[0:1], -1, 0
	v_writelane_b32 v250, s0, 6
	s_nop 1
	v_writelane_b32 v250, s1, 7
	s_cmpk_gt_i32 s61, 0x8ff
	s_cselect_b64 s[0:1], -1, 0
	v_writelane_b32 v250, s0, 8
	s_nop 1
	v_writelane_b32 v250, s1, 9
	s_cmpk_gt_i32 s61, 0x93f
	s_cselect_b64 s[0:1], -1, 0
	v_writelane_b32 v250, s0, 10
	s_nop 1
	v_writelane_b32 v250, s1, 11
	s_cmpk_gt_i32 s61, 0x97f
	s_cselect_b64 s[0:1], -1, 0
	v_writelane_b32 v250, s0, 12
	s_nop 1
	v_writelane_b32 v250, s1, 13
	s_cmpk_gt_i32 s61, 0x9bf
	s_cselect_b64 s[0:1], -1, 0
	v_writelane_b32 v250, s0, 14
	s_nop 1
	v_writelane_b32 v250, s1, 15
	s_cmpk_gt_i32 s61, 0x9ff
	s_cselect_b64 s[0:1], -1, 0
	v_writelane_b32 v250, s0, 16
	s_nop 1
	v_writelane_b32 v250, s1, 17
	s_cmpk_gt_i32 s61, 0xa3f
	s_cselect_b64 s[0:1], -1, 0
	v_writelane_b32 v250, s0, 18
	s_nop 1
	v_writelane_b32 v250, s1, 19
	s_cmpk_gt_i32 s61, 0xa7f
	s_cselect_b64 s[0:1], -1, 0
	v_writelane_b32 v250, s0, 20
	s_nop 1
	v_writelane_b32 v250, s1, 21
	s_cmpk_gt_i32 s61, 0xabf
	s_cselect_b64 s[0:1], -1, 0
	v_writelane_b32 v250, s0, 22
	s_nop 1
	v_writelane_b32 v250, s1, 23
	s_cmpk_gt_i32 s61, 0xaff
	s_cselect_b64 s[0:1], -1, 0
	v_writelane_b32 v250, s0, 24
	s_nop 1
	v_writelane_b32 v250, s1, 25
	s_cmpk_gt_i32 s61, 0xb3f
	s_cselect_b64 s[0:1], -1, 0
	v_writelane_b32 v250, s0, 26
	s_nop 1
	v_writelane_b32 v250, s1, 27
	s_cmpk_gt_i32 s61, 0xb7f
	s_cselect_b64 s[0:1], -1, 0
	v_writelane_b32 v250, s0, 28
	s_nop 1
	v_writelane_b32 v250, s1, 29
	s_cmpk_gt_i32 s61, 0xbbf
	s_cselect_b64 s[0:1], -1, 0
	v_writelane_b32 v250, s0, 30
	s_nop 1
	v_writelane_b32 v250, s1, 31
	s_cmpk_gt_i32 s61, 0xbff
	s_cselect_b64 s[52:53], -1, 0
	s_cmpk_gt_i32 s61, 0xc3f
	s_cselect_b64 s[50:51], -1, 0
	s_cmpk_gt_i32 s61, 0xc7f
	s_cselect_b64 s[48:49], -1, 0
	s_cmpk_gt_i32 s61, 0xcbf
	s_cselect_b64 s[46:47], -1, 0
	s_cmpk_gt_i32 s61, 0xcff
	s_cselect_b64 s[42:43], -1, 0
	s_cmpk_gt_i32 s61, 0xd3f
	s_cselect_b64 s[40:41], -1, 0
	s_cmpk_gt_i32 s61, 0xd7f
	s_cselect_b64 s[38:39], -1, 0
	s_cmpk_gt_i32 s61, 0xdbf
	s_cselect_b64 s[82:83], -1, 0
	s_cmpk_gt_i32 s61, 0xdff
	s_cselect_b64 s[96:97], -1, 0
	s_cmpk_gt_i32 s61, 0xe3f
	s_cselect_b64 s[94:95], -1, 0
	s_cmpk_gt_i32 s61, 0xe7f
	s_cselect_b64 s[92:93], -1, 0
	s_cmpk_gt_i32 s61, 0xebf
	s_cselect_b64 s[76:77], -1, 0
	s_cmpk_gt_i32 s61, 0xeff
	s_cselect_b64 s[90:91], -1, 0
	s_cmpk_gt_i32 s61, 0xf3f
	s_cselect_b64 s[88:89], -1, 0
	s_cmpk_gt_i32 s61, 0xf7f
	s_cselect_b64 s[86:87], -1, 0
	s_cmpk_gt_i32 s61, 0xfbf
	s_cselect_b64 s[84:85], -1, 0
	s_waitcnt vmcnt(0)
; #define LAS __attribute__((address_space(3)))
; __device__ __forceinline__ unsigned sortable(float f) { const unsigned b = __float_as_uint(f); return (b & 0x80000000u) ? ~b : (b | 0x80000000u); }
;     ...
;       LAS float* srow = sc + wid * 4096;
; #pragma unroll
;       for (int r = 0; r < 64; ++r) { u[r] = 0u; if (r * 64 < n) { const float f = srow[r * 64 + lane]; u[r] = (r * 64 + lane < n) ? sortable(f) : 0u; } }
;       const int nreg = (n + 63) >> 6;
	v_lshl_add_u32 v0, v163, 2, s60
	v_sub_u32_e32 v2, s61, v163
	ds_read_b32 v6, v0
	ds_read_b32 v5, v0 offset:256
	ds_read_b32 v8, v0 offset:512
	ds_read_b32 v7, v0 offset:768
	ds_read_b32 v10, v0 offset:1024
	ds_read_b32 v9, v0 offset:1280
	ds_read_b32 v12, v0 offset:1536
	ds_read_b32 v11, v0 offset:1792
	ds_read_b32 v14, v0 offset:2048
	ds_read_b32 v13, v0 offset:2304
	ds_read_b32 v16, v0 offset:2560
	ds_read_b32 v15, v0 offset:2816
	ds_read_b32 v18, v0 offset:3072
	ds_read_b32 v17, v0 offset:3328
	ds_read_b32 v20, v0 offset:3584
	s_waitcnt lgkmcnt(0)
	s_cmpk_lt_i32 s61, 0x3c0
	s_cbranch_scc1 .Ludsa_last0
	ds_read_b32 v19, v0 offset:3840
	ds_read_b32 v22, v0 offset:4096
	ds_read_b32 v21, v0 offset:4352
	ds_read_b32 v24, v0 offset:4608
	ds_read_b32 v23, v0 offset:4864
	ds_read_b32 v26, v0 offset:5120
	ds_read_b32 v25, v0 offset:5376
	ds_read_b32 v28, v0 offset:5632
	ds_read_b32 v27, v0 offset:5888
	ds_read_b32 v30, v0 offset:6144
	ds_read_b32 v29, v0 offset:6400
	ds_read_b32 v32, v0 offset:6656
	ds_read_b32 v31, v0 offset:6912
	ds_read_b32 v34, v0 offset:7168
	ds_read_b32 v33, v0 offset:7424
	v_cmp_le_i32_e32 vcc, 0, v2
	v_ashrrev_i32_e32 v4, 31, v6
	v_or_b32_e32 v4, 0x80000000, v4
	v_xor_b32_e32 v6, v4, v6
	v_cndmask_b32_e32 v6, 0, v6, vcc
	v_cmp_le_i32_e32 vcc, 64, v2
	v_ashrrev_i32_e32 v3, 31, v5
	v_or_b32_e32 v3, 0x80000000, v3
	v_xor_b32_e32 v5, v3, v5
	v_cndmask_b32_e32 v5, 0, v5, vcc
	v_cmp_le_i32_e32 vcc, 0x80, v2
	v_ashrrev_i32_e32 v4, 31, v8
	v_or_b32_e32 v4, 0x80000000, v4
	v_xor_b32_e32 v8, v4, v8
	v_cndmask_b32_e32 v8, 0, v8, vcc
	v_cmp_le_i32_e32 vcc, 0xc0, v2
	v_ashrrev_i32_e32 v3, 31, v7
	v_or_b32_e32 v3, 0x80000000, v3
	v_xor_b32_e32 v7, v3, v7
	v_cndmask_b32_e32 v7, 0, v7, vcc
	v_cmp_le_i32_e32 vcc, 0x100, v2
	v_ashrrev_i32_e32 v4, 31, v10
	v_or_b32_e32 v4, 0x80000000, v4
	v_xor_b32_e32 v10, v4, v10
	v_cndmask_b32_e32 v10, 0, v10, vcc
	v_cmp_le_i32_e32 vcc, 0x140, v2
	v_ashrrev_i32_e32 v3, 31, v9
	v_or_b32_e32 v3, 0x80000000, v3
	v_xor_b32_e32 v9, v3, v9
	v_cndmask_b32_e32 v9, 0, v9, vcc
	v_cmp_le_i32_e32 vcc, 0x180, v2
	v_ashrrev_i32_e32 v4, 31, v12
	v_or_b32_e32 v4, 0x80000000, v4
	v_xor_b32_e32 v12, v4, v12
	v_cndmask_b32_e32 v12, 0, v12, vcc
	v_cmp_le_i32_e32 vcc, 0x1c0, v2
	v_ashrrev_i32_e32 v3, 31, v11
	v_or_b32_e32 v3, 0x80000000, v3
	v_xor_b32_e32 v11, v3, v11
	v_cndmask_b32_e32 v11, 0, v11, vcc
	v_cmp_le_i32_e32 vcc, 0x200, v2
	v_ashrrev_i32_e32 v4, 31, v14
	v_or_b32_e32 v4, 0x80000000, v4
	v_xor_b32_e32 v14, v4, v14
	v_cndmask_b32_e32 v14, 0, v14, vcc
	v_cmp_le_i32_e32 vcc, 0x240, v2
	v_ashrrev_i32_e32 v3, 31, v13
	v_or_b32_e32 v3, 0x80000000, v3
	v_xor_b32_e32 v13, v3, v13
	v_cndmask_b32_e32 v13, 0, v13, vcc
	v_cmp_le_i32_e32 vcc, 0x280, v2
	v_ashrrev_i32_e32 v4, 31, v16
	v_or_b32_e32 v4, 0x80000000, v4
	v_xor_b32_e32 v16, v4, v16
	v_cndmask_b32_e32 v16, 0, v16, vcc
	v_cmp_le_i32_e32 vcc, 0x2c0, v2
	v_ashrrev_i32_e32 v3, 31, v15
	v_or_b32_e32 v3, 0x80000000, v3
	v_xor_b32_e32 v15, v3, v15
	v_cndmask_b32_e32 v15, 0, v15, vcc
	v_cmp_le_i32_e32 vcc, 0x300, v2
	v_ashrrev_i32_e32 v4, 31, v18
	v_or_b32_e32 v4, 0x80000000, v4
	v_xor_b32_e32 v18, v4, v18
	v_cndmask_b32_e32 v18, 0, v18, vcc
	v_cmp_le_i32_e32 vcc, 0x340, v2
	v_ashrrev_i32_e32 v3, 31, v17
	v_or_b32_e32 v3, 0x80000000, v3
	v_xor_b32_e32 v17, v3, v17
	v_cndmask_b32_e32 v17, 0, v17, vcc
	v_cmp_le_i32_e32 vcc, 0x380, v2
	v_ashrrev_i32_e32 v4, 31, v20
	v_or_b32_e32 v4, 0x80000000, v4
	v_xor_b32_e32 v20, v4, v20
	v_cndmask_b32_e32 v20, 0, v20, vcc
	s_waitcnt lgkmcnt(0)
	s_cmpk_lt_i32 s61, 0x780
	s_cbranch_scc1 .Ludsa_last1
	ds_read_b32 v36, v0 offset:7680
	ds_read_b32 v35, v0 offset:7936
	ds_read_b32 v38, v0 offset:8192
	ds_read_b32 v37, v0 offset:8448
	ds_read_b32 v40, v0 offset:8704
	ds_read_b32 v39, v0 offset:8960
	ds_read_b32 v42, v0 offset:9216
	ds_read_b32 v41, v0 offset:9472
	ds_read_b32 v44, v0 offset:9728
	ds_read_b32 v43, v0 offset:9984
	ds_read_b32 v46, v0 offset:10240
	ds_read_b32 v45, v0 offset:10496
	ds_read_b32 v48, v0 offset:10752
	ds_read_b32 v47, v0 offset:11008
	ds_read_b32 v50, v0 offset:11264
	v_cmp_le_i32_e32 vcc, 0x3c0, v2
	v_ashrrev_i32_e32 v3, 31, v19
	v_or_b32_e32 v3, 0x80000000, v3
	v_xor_b32_e32 v19, v3, v19
	v_cndmask_b32_e32 v19, 0, v19, vcc
	v_cmp_le_i32_e32 vcc, 0x400, v2
	v_ashrrev_i32_e32 v4, 31, v22
	v_or_b32_e32 v4, 0x80000000, v4
	v_xor_b32_e32 v22, v4, v22
	v_cndmask_b32_e32 v22, 0, v22, vcc
	v_cmp_le_i32_e32 vcc, 0x440, v2
	v_ashrrev_i32_e32 v3, 31, v21
	v_or_b32_e32 v3, 0x80000000, v3
	v_xor_b32_e32 v21, v3, v21
	v_cndmask_b32_e32 v21, 0, v21, vcc
	v_cmp_le_i32_e32 vcc, 0x480, v2
	v_ashrrev_i32_e32 v4, 31, v24
	v_or_b32_e32 v4, 0x80000000, v4
	v_xor_b32_e32 v24, v4, v24
	v_cndmask_b32_e32 v24, 0, v24, vcc
	v_cmp_le_i32_e32 vcc, 0x4c0, v2
	v_ashrrev_i32_e32 v3, 31, v23
	v_or_b32_e32 v3, 0x80000000, v3
	v_xor_b32_e32 v23, v3, v23
	v_cndmask_b32_e32 v23, 0, v23, vcc
	v_cmp_le_i32_e32 vcc, 0x500, v2
	v_ashrrev_i32_e32 v4, 31, v26
	v_or_b32_e32 v4, 0x80000000, v4
	v_xor_b32_e32 v26, v4, v26
	v_cndmask_b32_e32 v26, 0, v26, vcc
	v_cmp_le_i32_e32 vcc, 0x540, v2
	v_ashrrev_i32_e32 v3, 31, v25
	v_or_b32_e32 v3, 0x80000000, v3
	v_xor_b32_e32 v25, v3, v25
	v_cndmask_b32_e32 v25, 0, v25, vcc
	v_cmp_le_i32_e32 vcc, 0x580, v2
	v_ashrrev_i32_e32 v4, 31, v28
	v_or_b32_e32 v4, 0x80000000, v4
	v_xor_b32_e32 v28, v4, v28
	v_cndmask_b32_e32 v28, 0, v28, vcc
	v_cmp_le_i32_e32 vcc, 0x5c0, v2
	v_ashrrev_i32_e32 v3, 31, v27
	v_or_b32_e32 v3, 0x80000000, v3
	v_xor_b32_e32 v27, v3, v27
	v_cndmask_b32_e32 v27, 0, v27, vcc
	v_cmp_le_i32_e32 vcc, 0x600, v2
	v_ashrrev_i32_e32 v4, 31, v30
	v_or_b32_e32 v4, 0x80000000, v4
	v_xor_b32_e32 v30, v4, v30
	v_cndmask_b32_e32 v30, 0, v30, vcc
	v_cmp_le_i32_e32 vcc, 0x640, v2
	v_ashrrev_i32_e32 v3, 31, v29
	v_or_b32_e32 v3, 0x80000000, v3
	v_xor_b32_e32 v29, v3, v29
	v_cndmask_b32_e32 v29, 0, v29, vcc
	v_cmp_le_i32_e32 vcc, 0x680, v2
	v_ashrrev_i32_e32 v4, 31, v32
	v_or_b32_e32 v4, 0x80000000, v4
	v_xor_b32_e32 v32, v4, v32
	v_cndmask_b32_e32 v32, 0, v32, vcc
	v_cmp_le_i32_e32 vcc, 0x6c0, v2
	v_ashrrev_i32_e32 v3, 31, v31
	v_or_b32_e32 v3, 0x80000000, v3
	v_xor_b32_e32 v31, v3, v31
	v_cndmask_b32_e32 v31, 0, v31, vcc
	v_cmp_le_i32_e32 vcc, 0x700, v2
	v_ashrrev_i32_e32 v4, 31, v34
	v_or_b32_e32 v4, 0x80000000, v4
	v_xor_b32_e32 v34, v4, v34
	v_cndmask_b32_e32 v34, 0, v34, vcc
	v_cmp_le_i32_e32 vcc, 0x740, v2
	v_ashrrev_i32_e32 v3, 31, v33
	v_or_b32_e32 v3, 0x80000000, v3
	v_xor_b32_e32 v33, v3, v33
	v_cndmask_b32_e32 v33, 0, v33, vcc
	s_waitcnt lgkmcnt(0)
	s_cmpk_lt_i32 s61, 0xb40
	s_cbranch_scc1 .Ludsa_last2
; #define LAS __attribute__((address_space(3)))
; __device__ __forceinline__ unsigned sortable(float f) { const unsigned b = __float_as_uint(f); return (b & 0x80000000u) ? ~b : (b | 0x80000000u); }
;     ...
;       LAS float* srow = sc + wid * 4096;
; #pragma unroll
;       for (int r = 0; r < 64; ++r) { u[r] = 0u; if (r * 64 < n) { const float f = srow[r * 64 + lane]; u[r] = (r * 64 + lane < n) ? sortable(f) : 0u; } }
;       const int nreg = (n + 63) >> 6;
	ds_read_b32 v49, v0 offset:11520
	ds_read_b32 v52, v0 offset:11776
	ds_read_b32 v51, v0 offset:12032
	ds_read_b32 v54, v0 offset:12288
	ds_read_b32 v53, v0 offset:12544
	ds_read_b32 v56, v0 offset:12800
	ds_read_b32 v55, v0 offset:13056
	ds_read_b32 v58, v0 offset:13312
	ds_read_b32 v57, v0 offset:13568
	ds_read_b32 v60, v0 offset:13824
	ds_read_b32 v59, v0 offset:14080
	ds_read_b32 v62, v0 offset:14336
	ds_read_b32 v61, v0 offset:14592
	ds_read_b32 v64, v0 offset:14848
	ds_read_b32 v63, v0 offset:15104
	v_cmp_le_i32_e32 vcc, 0x780, v2
	v_ashrrev_i32_e32 v4, 31, v36
	v_or_b32_e32 v4, 0x80000000, v4
	v_xor_b32_e32 v36, v4, v36
	v_cndmask_b32_e32 v36, 0, v36, vcc
	v_cmp_le_i32_e32 vcc, 0x7c0, v2
	v_ashrrev_i32_e32 v3, 31, v35
	v_or_b32_e32 v3, 0x80000000, v3
	v_xor_b32_e32 v35, v3, v35
	v_cndmask_b32_e32 v35, 0, v35, vcc
	v_cmp_le_i32_e32 vcc, 0x800, v2
	v_ashrrev_i32_e32 v4, 31, v38
	v_or_b32_e32 v4, 0x80000000, v4
	v_xor_b32_e32 v38, v4, v38
	v_cndmask_b32_e32 v38, 0, v38, vcc
	v_cmp_le_i32_e32 vcc, 0x840, v2
	v_ashrrev_i32_e32 v3, 31, v37
	v_or_b32_e32 v3, 0x80000000, v3
	v_xor_b32_e32 v37, v3, v37
	v_cndmask_b32_e32 v37, 0, v37, vcc
	v_cmp_le_i32_e32 vcc, 0x880, v2
	v_ashrrev_i32_e32 v4, 31, v40
	v_or_b32_e32 v4, 0x80000000, v4
	v_xor_b32_e32 v40, v4, v40
	v_cndmask_b32_e32 v40, 0, v40, vcc
	v_cmp_le_i32_e32 vcc, 0x8c0, v2
	v_ashrrev_i32_e32 v3, 31, v39
	v_or_b32_e32 v3, 0x80000000, v3
	v_xor_b32_e32 v39, v3, v39
	v_cndmask_b32_e32 v39, 0, v39, vcc
	v_cmp_le_i32_e32 vcc, 0x900, v2
	v_ashrrev_i32_e32 v4, 31, v42
	v_or_b32_e32 v4, 0x80000000, v4
	v_xor_b32_e32 v42, v4, v42
	v_cndmask_b32_e32 v42, 0, v42, vcc
	v_cmp_le_i32_e32 vcc, 0x940, v2
	v_ashrrev_i32_e32 v3, 31, v41
	v_or_b32_e32 v3, 0x80000000, v3
	v_xor_b32_e32 v41, v3, v41
	v_cndmask_b32_e32 v41, 0, v41, vcc
	v_cmp_le_i32_e32 vcc, 0x980, v2
	v_ashrrev_i32_e32 v4, 31, v44
	v_or_b32_e32 v4, 0x80000000, v4
	v_xor_b32_e32 v44, v4, v44
	v_cndmask_b32_e32 v44, 0, v44, vcc
	v_cmp_le_i32_e32 vcc, 0x9c0, v2
	v_ashrrev_i32_e32 v3, 31, v43
	v_or_b32_e32 v3, 0x80000000, v3
	v_xor_b32_e32 v43, v3, v43
	v_cndmask_b32_e32 v43, 0, v43, vcc
	v_cmp_le_i32_e32 vcc, 0xa00, v2
	v_ashrrev_i32_e32 v4, 31, v46
	v_or_b32_e32 v4, 0x80000000, v4
	v_xor_b32_e32 v46, v4, v46
	v_cndmask_b32_e32 v46, 0, v46, vcc
	v_cmp_le_i32_e32 vcc, 0xa40, v2
	v_ashrrev_i32_e32 v3, 31, v45
	v_or_b32_e32 v3, 0x80000000, v3
	v_xor_b32_e32 v45, v3, v45
	v_cndmask_b32_e32 v45, 0, v45, vcc
	v_cmp_le_i32_e32 vcc, 0xa80, v2
	v_ashrrev_i32_e32 v4, 31, v48
	v_or_b32_e32 v4, 0x80000000, v4
	v_xor_b32_e32 v48, v4, v48
	v_cndmask_b32_e32 v48, 0, v48, vcc
	v_cmp_le_i32_e32 vcc, 0xac0, v2
	v_ashrrev_i32_e32 v3, 31, v47
	v_or_b32_e32 v3, 0x80000000, v3
	v_xor_b32_e32 v47, v3, v47
	v_cndmask_b32_e32 v47, 0, v47, vcc
	v_cmp_le_i32_e32 vcc, 0xb00, v2
	v_ashrrev_i32_e32 v4, 31, v50
	v_or_b32_e32 v4, 0x80000000, v4
	v_xor_b32_e32 v50, v4, v50
	v_cndmask_b32_e32 v50, 0, v50, vcc
	s_waitcnt lgkmcnt(0)
	s_cmpk_lt_i32 s61, 0xf00
	s_cbranch_scc1 .Ludsa_last3
	ds_read_b32 v66, v0 offset:15360
	ds_read_b32 v65, v0 offset:15616
	ds_read_b32 v68, v0 offset:15872
	ds_read_b32 v67, v0 offset:16128
	v_cmp_le_i32_e32 vcc, 0xb40, v2
	v_ashrrev_i32_e32 v3, 31, v49
	v_or_b32_e32 v3, 0x80000000, v3
	v_xor_b32_e32 v49, v3, v49
	v_cndmask_b32_e32 v49, 0, v49, vcc
	v_cmp_le_i32_e32 vcc, 0xb80, v2
	v_ashrrev_i32_e32 v4, 31, v52
	v_or_b32_e32 v4, 0x80000000, v4
	v_xor_b32_e32 v52, v4, v52
	v_cndmask_b32_e32 v52, 0, v52, vcc
	v_cmp_le_i32_e32 vcc, 0xbc0, v2
	v_ashrrev_i32_e32 v3, 31, v51
	v_or_b32_e32 v3, 0x80000000, v3
	v_xor_b32_e32 v51, v3, v51
	v_cndmask_b32_e32 v51, 0, v51, vcc
	v_cmp_le_i32_e32 vcc, 0xc00, v2
	v_ashrrev_i32_e32 v4, 31, v54
	v_or_b32_e32 v4, 0x80000000, v4
	v_xor_b32_e32 v54, v4, v54
	v_cndmask_b32_e32 v54, 0, v54, vcc
	v_cmp_le_i32_e32 vcc, 0xc40, v2
	v_ashrrev_i32_e32 v3, 31, v53
	v_or_b32_e32 v3, 0x80000000, v3
	v_xor_b32_e32 v53, v3, v53
	v_cndmask_b32_e32 v53, 0, v53, vcc
	v_cmp_le_i32_e32 vcc, 0xc80, v2
	v_ashrrev_i32_e32 v4, 31, v56
	v_or_b32_e32 v4, 0x80000000, v4
	v_xor_b32_e32 v56, v4, v56
	v_cndmask_b32_e32 v56, 0, v56, vcc
	v_cmp_le_i32_e32 vcc, 0xcc0, v2
	v_ashrrev_i32_e32 v3, 31, v55
	v_or_b32_e32 v3, 0x80000000, v3
	v_xor_b32_e32 v55, v3, v55
	v_cndmask_b32_e32 v55, 0, v55, vcc
	v_cmp_le_i32_e32 vcc, 0xd00, v2
	v_ashrrev_i32_e32 v4, 31, v58
	v_or_b32_e32 v4, 0x80000000, v4
	v_xor_b32_e32 v58, v4, v58
	v_cndmask_b32_e32 v58, 0, v58, vcc
	v_cmp_le_i32_e32 vcc, 0xd40, v2
	v_ashrrev_i32_e32 v3, 31, v57
	v_or_b32_e32 v3, 0x80000000, v3
	v_xor_b32_e32 v57, v3, v57
	v_cndmask_b32_e32 v57, 0, v57, vcc
	v_cmp_le_i32_e32 vcc, 0xd80, v2
	v_ashrrev_i32_e32 v4, 31, v60
	v_or_b32_e32 v4, 0x80000000, v4
	v_xor_b32_e32 v60, v4, v60
	v_cndmask_b32_e32 v60, 0, v60, vcc
	v_cmp_le_i32_e32 vcc, 0xdc0, v2
	v_ashrrev_i32_e32 v3, 31, v59
	v_or_b32_e32 v3, 0x80000000, v3
	v_xor_b32_e32 v59, v3, v59
	v_cndmask_b32_e32 v59, 0, v59, vcc
	v_cmp_le_i32_e32 vcc, 0xe00, v2
	v_ashrrev_i32_e32 v4, 31, v62
	v_or_b32_e32 v4, 0x80000000, v4
	v_xor_b32_e32 v62, v4, v62
	v_cndmask_b32_e32 v62, 0, v62, vcc
	v_cmp_le_i32_e32 vcc, 0xe40, v2
	v_ashrrev_i32_e32 v3, 31, v61
	v_or_b32_e32 v3, 0x80000000, v3
	v_xor_b32_e32 v61, v3, v61
	v_cndmask_b32_e32 v61, 0, v61, vcc
	v_cmp_le_i32_e32 vcc, 0xe80, v2
	v_ashrrev_i32_e32 v4, 31, v64
	v_or_b32_e32 v4, 0x80000000, v4
	v_xor_b32_e32 v64, v4, v64
	v_cndmask_b32_e32 v64, 0, v64, vcc
	v_cmp_le_i32_e32 vcc, 0xec0, v2
	v_ashrrev_i32_e32 v3, 31, v63
	v_or_b32_e32 v3, 0x80000000, v3
	v_xor_b32_e32 v63, v3, v63
	v_cndmask_b32_e32 v63, 0, v63, vcc
	s_waitcnt lgkmcnt(0)
	v_cmp_le_i32_e32 vcc, 0xf00, v2
	v_ashrrev_i32_e32 v4, 31, v66
	v_or_b32_e32 v4, 0x80000000, v4
	v_xor_b32_e32 v66, v4, v66
	v_cndmask_b32_e32 v66, 0, v66, vcc
	v_cmp_le_i32_e32 vcc, 0xf40, v2
	v_ashrrev_i32_e32 v3, 31, v65
	v_or_b32_e32 v3, 0x80000000, v3
	v_xor_b32_e32 v65, v3, v65
	v_cndmask_b32_e32 v65, 0, v65, vcc
	v_cmp_le_i32_e32 vcc, 0xf80, v2
	v_ashrrev_i32_e32 v4, 31, v68
	v_or_b32_e32 v4, 0x80000000, v4
	v_xor_b32_e32 v68, v4, v68
	v_cndmask_b32_e32 v68, 0, v68, vcc
	v_cmp_le_i32_e32 vcc, 0xfc0, v2
	v_ashrrev_i32_e32 v3, 31, v67
	v_or_b32_e32 v3, 0x80000000, v3
	v_xor_b32_e32 v67, v3, v67
	v_cndmask_b32_e32 v67, 0, v67, vcc
	s_branch .Ludsa_done
; #define LAS __attribute__((address_space(3)))
; __device__ __forceinline__ unsigned sortable(float f) { const unsigned b = __float_as_uint(f); return (b & 0x80000000u) ? ~b : (b | 0x80000000u); }
;     ...
;       LAS float* srow = sc + wid * 4096;
; #pragma unroll
;       for (int r = 0; r < 64; ++r) { u[r] = 0u; if (r * 64 < n) { const float f = srow[r * 64 + lane]; u[r] = (r * 64 + lane < n) ? sortable(f) : 0u; } }
;       const int nreg = (n + 63) >> 6;
.Ludsa_last0:
	v_cmp_le_i32_e32 vcc, 0, v2
	v_ashrrev_i32_e32 v4, 31, v6
	v_or_b32_e32 v4, 0x80000000, v4
	v_xor_b32_e32 v6, v4, v6
	v_cndmask_b32_e32 v6, 0, v6, vcc
	v_cmp_le_i32_e32 vcc, 64, v2
	v_ashrrev_i32_e32 v3, 31, v5
	v_or_b32_e32 v3, 0x80000000, v3
	v_xor_b32_e32 v5, v3, v5
	v_cndmask_b32_e32 v5, 0, v5, vcc
	v_cmp_le_i32_e32 vcc, 0x80, v2
	v_ashrrev_i32_e32 v4, 31, v8
	v_or_b32_e32 v4, 0x80000000, v4
	v_xor_b32_e32 v8, v4, v8
	v_cndmask_b32_e32 v8, 0, v8, vcc
	v_cmp_le_i32_e32 vcc, 0xc0, v2
	v_ashrrev_i32_e32 v3, 31, v7
	v_or_b32_e32 v3, 0x80000000, v3
	v_xor_b32_e32 v7, v3, v7
	v_cndmask_b32_e32 v7, 0, v7, vcc
	v_cmp_le_i32_e32 vcc, 0x100, v2
	v_ashrrev_i32_e32 v4, 31, v10
	v_or_b32_e32 v4, 0x80000000, v4
	v_xor_b32_e32 v10, v4, v10
	v_cndmask_b32_e32 v10, 0, v10, vcc
	v_cmp_le_i32_e32 vcc, 0x140, v2
	v_ashrrev_i32_e32 v3, 31, v9
	v_or_b32_e32 v3, 0x80000000, v3
	v_xor_b32_e32 v9, v3, v9
	v_cndmask_b32_e32 v9, 0, v9, vcc
	v_cmp_le_i32_e32 vcc, 0x180, v2
	v_ashrrev_i32_e32 v4, 31, v12
	v_or_b32_e32 v4, 0x80000000, v4
	v_xor_b32_e32 v12, v4, v12
	v_cndmask_b32_e32 v12, 0, v12, vcc
	v_cmp_le_i32_e32 vcc, 0x1c0, v2
	v_ashrrev_i32_e32 v3, 31, v11
	v_or_b32_e32 v3, 0x80000000, v3
	v_xor_b32_e32 v11, v3, v11
	v_cndmask_b32_e32 v11, 0, v11, vcc
	v_cmp_le_i32_e32 vcc, 0x200, v2
	v_ashrrev_i32_e32 v4, 31, v14
	v_or_b32_e32 v4, 0x80000000, v4
	v_xor_b32_e32 v14, v4, v14
	v_cndmask_b32_e32 v14, 0, v14, vcc
	v_cmp_le_i32_e32 vcc, 0x240, v2
	v_ashrrev_i32_e32 v3, 31, v13
	v_or_b32_e32 v3, 0x80000000, v3
	v_xor_b32_e32 v13, v3, v13
	v_cndmask_b32_e32 v13, 0, v13, vcc
	v_cmp_le_i32_e32 vcc, 0x280, v2
	v_ashrrev_i32_e32 v4, 31, v16
	v_or_b32_e32 v4, 0x80000000, v4
	v_xor_b32_e32 v16, v4, v16
	v_cndmask_b32_e32 v16, 0, v16, vcc
	v_cmp_le_i32_e32 vcc, 0x2c0, v2
	v_ashrrev_i32_e32 v3, 31, v15
	v_or_b32_e32 v3, 0x80000000, v3
	v_xor_b32_e32 v15, v3, v15
	v_cndmask_b32_e32 v15, 0, v15, vcc
	v_cmp_le_i32_e32 vcc, 0x300, v2
	v_ashrrev_i32_e32 v4, 31, v18
	v_or_b32_e32 v4, 0x80000000, v4
	v_xor_b32_e32 v18, v4, v18
	v_cndmask_b32_e32 v18, 0, v18, vcc
	v_cmp_le_i32_e32 vcc, 0x340, v2
	v_ashrrev_i32_e32 v3, 31, v17
	v_or_b32_e32 v3, 0x80000000, v3
	v_xor_b32_e32 v17, v3, v17
	v_cndmask_b32_e32 v17, 0, v17, vcc
	v_cmp_le_i32_e32 vcc, 0x380, v2
	v_ashrrev_i32_e32 v4, 31, v20
	v_or_b32_e32 v4, 0x80000000, v4
	v_xor_b32_e32 v20, v4, v20
	v_cndmask_b32_e32 v20, 0, v20, vcc
	v_mov_b32_e32 v19, 0
	v_mov_b32_e32 v22, 0
	v_mov_b32_e32 v21, 0
	v_mov_b32_e32 v24, 0
	v_mov_b32_e32 v23, 0
	v_mov_b32_e32 v26, 0
	v_mov_b32_e32 v25, 0
	v_mov_b32_e32 v28, 0
	v_mov_b32_e32 v27, 0
	v_mov_b32_e32 v30, 0
	v_mov_b32_e32 v29, 0
	v_mov_b32_e32 v32, 0
	v_mov_b32_e32 v31, 0
	v_mov_b32_e32 v34, 0
	v_mov_b32_e32 v33, 0
	v_mov_b32_e32 v36, 0
	v_mov_b32_e32 v35, 0
	v_mov_b32_e32 v38, 0
	v_mov_b32_e32 v37, 0
	v_mov_b32_e32 v40, 0
	v_mov_b32_e32 v39, 0
	v_mov_b32_e32 v42, 0
	v_mov_b32_e32 v41, 0
	v_mov_b32_e32 v44, 0
	v_mov_b32_e32 v43, 0
	v_mov_b32_e32 v46, 0
	v_mov_b32_e32 v45, 0
	v_mov_b32_e32 v48, 0
	v_mov_b32_e32 v47, 0
	v_mov_b32_e32 v50, 0
	v_mov_b32_e32 v49, 0
	v_mov_b32_e32 v52, 0
	v_mov_b32_e32 v51, 0
	v_mov_b32_e32 v54, 0
	v_mov_b32_e32 v53, 0
	v_mov_b32_e32 v56, 0
	v_mov_b32_e32 v55, 0
	v_mov_b32_e32 v58, 0
	v_mov_b32_e32 v57, 0
	v_mov_b32_e32 v60, 0
	v_mov_b32_e32 v59, 0
	v_mov_b32_e32 v62, 0
	v_mov_b32_e32 v61, 0
	v_mov_b32_e32 v64, 0
	v_mov_b32_e32 v63, 0
	v_mov_b32_e32 v66, 0
	v_mov_b32_e32 v65, 0
	v_mov_b32_e32 v68, 0
	v_mov_b32_e32 v67, 0
	s_branch .Ludsa_done
.Ludsa_last1:
	v_cmp_le_i32_e32 vcc, 0x3c0, v2
	v_ashrrev_i32_e32 v3, 31, v19
	v_or_b32_e32 v3, 0x80000000, v3
	v_xor_b32_e32 v19, v3, v19
	v_cndmask_b32_e32 v19, 0, v19, vcc
	v_cmp_le_i32_e32 vcc, 0x400, v2
	v_ashrrev_i32_e32 v4, 31, v22
	v_or_b32_e32 v4, 0x80000000, v4
	v_xor_b32_e32 v22, v4, v22
	v_cndmask_b32_e32 v22, 0, v22, vcc
	v_cmp_le_i32_e32 vcc, 0x440, v2
	v_ashrrev_i32_e32 v3, 31, v21
	v_or_b32_e32 v3, 0x80000000, v3
	v_xor_b32_e32 v21, v3, v21
	v_cndmask_b32_e32 v21, 0, v21, vcc
	v_cmp_le_i32_e32 vcc, 0x480, v2
	v_ashrrev_i32_e32 v4, 31, v24
	v_or_b32_e32 v4, 0x80000000, v4
	v_xor_b32_e32 v24, v4, v24
	v_cndmask_b32_e32 v24, 0, v24, vcc
	v_cmp_le_i32_e32 vcc, 0x4c0, v2
	v_ashrrev_i32_e32 v3, 31, v23
	v_or_b32_e32 v3, 0x80000000, v3
	v_xor_b32_e32 v23, v3, v23
	v_cndmask_b32_e32 v23, 0, v23, vcc
	v_cmp_le_i32_e32 vcc, 0x500, v2
	v_ashrrev_i32_e32 v4, 31, v26
	v_or_b32_e32 v4, 0x80000000, v4
	v_xor_b32_e32 v26, v4, v26
	v_cndmask_b32_e32 v26, 0, v26, vcc
	v_cmp_le_i32_e32 vcc, 0x540, v2
	v_ashrrev_i32_e32 v3, 31, v25
	v_or_b32_e32 v3, 0x80000000, v3
	v_xor_b32_e32 v25, v3, v25
	v_cndmask_b32_e32 v25, 0, v25, vcc
	v_cmp_le_i32_e32 vcc, 0x580, v2
	v_ashrrev_i32_e32 v4, 31, v28
	v_or_b32_e32 v4, 0x80000000, v4
	v_xor_b32_e32 v28, v4, v28
	v_cndmask_b32_e32 v28, 0, v28, vcc
	v_cmp_le_i32_e32 vcc, 0x5c0, v2
	v_ashrrev_i32_e32 v3, 31, v27
	v_or_b32_e32 v3, 0x80000000, v3
	v_xor_b32_e32 v27, v3, v27
	v_cndmask_b32_e32 v27, 0, v27, vcc
	v_cmp_le_i32_e32 vcc, 0x600, v2
	v_ashrrev_i32_e32 v4, 31, v30
	v_or_b32_e32 v4, 0x80000000, v4
	v_xor_b32_e32 v30, v4, v30
	v_cndmask_b32_e32 v30, 0, v30, vcc
	v_cmp_le_i32_e32 vcc, 0x640, v2
	v_ashrrev_i32_e32 v3, 31, v29
	v_or_b32_e32 v3, 0x80000000, v3
	v_xor_b32_e32 v29, v3, v29
	v_cndmask_b32_e32 v29, 0, v29, vcc
	v_cmp_le_i32_e32 vcc, 0x680, v2
	v_ashrrev_i32_e32 v4, 31, v32
	v_or_b32_e32 v4, 0x80000000, v4
	v_xor_b32_e32 v32, v4, v32
	v_cndmask_b32_e32 v32, 0, v32, vcc
	v_cmp_le_i32_e32 vcc, 0x6c0, v2
	v_ashrrev_i32_e32 v3, 31, v31
	v_or_b32_e32 v3, 0x80000000, v3
	v_xor_b32_e32 v31, v3, v31
	v_cndmask_b32_e32 v31, 0, v31, vcc
	v_cmp_le_i32_e32 vcc, 0x700, v2
	v_ashrrev_i32_e32 v4, 31, v34
	v_or_b32_e32 v4, 0x80000000, v4
	v_xor_b32_e32 v34, v4, v34
	v_cndmask_b32_e32 v34, 0, v34, vcc
	v_cmp_le_i32_e32 vcc, 0x740, v2
	v_ashrrev_i32_e32 v3, 31, v33
	v_or_b32_e32 v3, 0x80000000, v3
	v_xor_b32_e32 v33, v3, v33
	v_cndmask_b32_e32 v33, 0, v33, vcc
	v_mov_b32_e32 v36, 0
	v_mov_b32_e32 v35, 0
	v_mov_b32_e32 v38, 0
	v_mov_b32_e32 v37, 0
	v_mov_b32_e32 v40, 0
	v_mov_b32_e32 v39, 0
	v_mov_b32_e32 v42, 0
	v_mov_b32_e32 v41, 0
	v_mov_b32_e32 v44, 0
	v_mov_b32_e32 v43, 0
	v_mov_b32_e32 v46, 0
	v_mov_b32_e32 v45, 0
	v_mov_b32_e32 v48, 0
	v_mov_b32_e32 v47, 0
	v_mov_b32_e32 v50, 0
	v_mov_b32_e32 v49, 0
	v_mov_b32_e32 v52, 0
	v_mov_b32_e32 v51, 0
	v_mov_b32_e32 v54, 0
	v_mov_b32_e32 v53, 0
	v_mov_b32_e32 v56, 0
	v_mov_b32_e32 v55, 0
	v_mov_b32_e32 v58, 0
	v_mov_b32_e32 v57, 0
	v_mov_b32_e32 v60, 0
	v_mov_b32_e32 v59, 0
	v_mov_b32_e32 v62, 0
	v_mov_b32_e32 v61, 0
	v_mov_b32_e32 v64, 0
	v_mov_b32_e32 v63, 0
	v_mov_b32_e32 v66, 0
	v_mov_b32_e32 v65, 0
	v_mov_b32_e32 v68, 0
	v_mov_b32_e32 v67, 0
	s_branch .Ludsa_done
; #define LAS __attribute__((address_space(3)))
; __device__ __forceinline__ unsigned sortable(float f) { const unsigned b = __float_as_uint(f); return (b & 0x80000000u) ? ~b : (b | 0x80000000u); }
;     ...
;       LAS float* srow = sc + wid * 4096;
; #pragma unroll
;       for (int r = 0; r < 64; ++r) { u[r] = 0u; if (r * 64 < n) { const float f = srow[r * 64 + lane]; u[r] = (r * 64 + lane < n) ? sortable(f) : 0u; } }
;       const int nreg = (n + 63) >> 6;
.Ludsa_last2:
	v_cmp_le_i32_e32 vcc, 0x780, v2
	v_ashrrev_i32_e32 v4, 31, v36
	v_or_b32_e32 v4, 0x80000000, v4
	v_xor_b32_e32 v36, v4, v36
	v_cndmask_b32_e32 v36, 0, v36, vcc
	v_cmp_le_i32_e32 vcc, 0x7c0, v2
	v_ashrrev_i32_e32 v3, 31, v35
	v_or_b32_e32 v3, 0x80000000, v3
	v_xor_b32_e32 v35, v3, v35
	v_cndmask_b32_e32 v35, 0, v35, vcc
	v_cmp_le_i32_e32 vcc, 0x800, v2
	v_ashrrev_i32_e32 v4, 31, v38
	v_or_b32_e32 v4, 0x80000000, v4
	v_xor_b32_e32 v38, v4, v38
	v_cndmask_b32_e32 v38, 0, v38, vcc
	v_cmp_le_i32_e32 vcc, 0x840, v2
	v_ashrrev_i32_e32 v3, 31, v37
	v_or_b32_e32 v3, 0x80000000, v3
	v_xor_b32_e32 v37, v3, v37
	v_cndmask_b32_e32 v37, 0, v37, vcc
	v_cmp_le_i32_e32 vcc, 0x880, v2
	v_ashrrev_i32_e32 v4, 31, v40
	v_or_b32_e32 v4, 0x80000000, v4
	v_xor_b32_e32 v40, v4, v40
	v_cndmask_b32_e32 v40, 0, v40, vcc
	v_cmp_le_i32_e32 vcc, 0x8c0, v2
	v_ashrrev_i32_e32 v3, 31, v39
	v_or_b32_e32 v3, 0x80000000, v3
	v_xor_b32_e32 v39, v3, v39
	v_cndmask_b32_e32 v39, 0, v39, vcc
	v_cmp_le_i32_e32 vcc, 0x900, v2
	v_ashrrev_i32_e32 v4, 31, v42
	v_or_b32_e32 v4, 0x80000000, v4
	v_xor_b32_e32 v42, v4, v42
	v_cndmask_b32_e32 v42, 0, v42, vcc
	v_cmp_le_i32_e32 vcc, 0x940, v2
	v_ashrrev_i32_e32 v3, 31, v41
	v_or_b32_e32 v3, 0x80000000, v3
	v_xor_b32_e32 v41, v3, v41
	v_cndmask_b32_e32 v41, 0, v41, vcc
	v_cmp_le_i32_e32 vcc, 0x980, v2
	v_ashrrev_i32_e32 v4, 31, v44
	v_or_b32_e32 v4, 0x80000000, v4
	v_xor_b32_e32 v44, v4, v44
	v_cndmask_b32_e32 v44, 0, v44, vcc
	v_cmp_le_i32_e32 vcc, 0x9c0, v2
	v_ashrrev_i32_e32 v3, 31, v43
	v_or_b32_e32 v3, 0x80000000, v3
	v_xor_b32_e32 v43, v3, v43
	v_cndmask_b32_e32 v43, 0, v43, vcc
	v_cmp_le_i32_e32 vcc, 0xa00, v2
	v_ashrrev_i32_e32 v4, 31, v46
	v_or_b32_e32 v4, 0x80000000, v4
	v_xor_b32_e32 v46, v4, v46
	v_cndmask_b32_e32 v46, 0, v46, vcc
	v_cmp_le_i32_e32 vcc, 0xa40, v2
	v_ashrrev_i32_e32 v3, 31, v45
	v_or_b32_e32 v3, 0x80000000, v3
	v_xor_b32_e32 v45, v3, v45
	v_cndmask_b32_e32 v45, 0, v45, vcc
	v_cmp_le_i32_e32 vcc, 0xa80, v2
	v_ashrrev_i32_e32 v4, 31, v48
	v_or_b32_e32 v4, 0x80000000, v4
	v_xor_b32_e32 v48, v4, v48
	v_cndmask_b32_e32 v48, 0, v48, vcc
	v_cmp_le_i32_e32 vcc, 0xac0, v2
	v_ashrrev_i32_e32 v3, 31, v47
	v_or_b32_e32 v3, 0x80000000, v3
	v_xor_b32_e32 v47, v3, v47
	v_cndmask_b32_e32 v47, 0, v47, vcc
	v_cmp_le_i32_e32 vcc, 0xb00, v2
	v_ashrrev_i32_e32 v4, 31, v50
	v_or_b32_e32 v4, 0x80000000, v4
	v_xor_b32_e32 v50, v4, v50
	v_cndmask_b32_e32 v50, 0, v50, vcc
	v_mov_b32_e32 v49, 0
	v_mov_b32_e32 v52, 0
	v_mov_b32_e32 v51, 0
	v_mov_b32_e32 v54, 0
	v_mov_b32_e32 v53, 0
	v_mov_b32_e32 v56, 0
	v_mov_b32_e32 v55, 0
	v_mov_b32_e32 v58, 0
	v_mov_b32_e32 v57, 0
	v_mov_b32_e32 v60, 0
	v_mov_b32_e32 v59, 0
	v_mov_b32_e32 v62, 0
	v_mov_b32_e32 v61, 0
	v_mov_b32_e32 v64, 0
	v_mov_b32_e32 v63, 0
	v_mov_b32_e32 v66, 0
	v_mov_b32_e32 v65, 0
	v_mov_b32_e32 v68, 0
	v_mov_b32_e32 v67, 0
	s_branch .Ludsa_done
.Ludsa_last3:
	v_cmp_le_i32_e32 vcc, 0xb40, v2
	v_ashrrev_i32_e32 v3, 31, v49
	v_or_b32_e32 v3, 0x80000000, v3
	v_xor_b32_e32 v49, v3, v49
	v_cndmask_b32_e32 v49, 0, v49, vcc
	v_cmp_le_i32_e32 vcc, 0xb80, v2
	v_ashrrev_i32_e32 v4, 31, v52
	v_or_b32_e32 v4, 0x80000000, v4
	v_xor_b32_e32 v52, v4, v52
	v_cndmask_b32_e32 v52, 0, v52, vcc
	v_cmp_le_i32_e32 vcc, 0xbc0, v2
	v_ashrrev_i32_e32 v3, 31, v51
	v_or_b32_e32 v3, 0x80000000, v3
	v_xor_b32_e32 v51, v3, v51
	v_cndmask_b32_e32 v51, 0, v51, vcc
	v_cmp_le_i32_e32 vcc, 0xc00, v2
	v_ashrrev_i32_e32 v4, 31, v54
	v_or_b32_e32 v4, 0x80000000, v4
	v_xor_b32_e32 v54, v4, v54
	v_cndmask_b32_e32 v54, 0, v54, vcc
	v_cmp_le_i32_e32 vcc, 0xc40, v2
	v_ashrrev_i32_e32 v3, 31, v53
	v_or_b32_e32 v3, 0x80000000, v3
	v_xor_b32_e32 v53, v3, v53
	v_cndmask_b32_e32 v53, 0, v53, vcc
	v_cmp_le_i32_e32 vcc, 0xc80, v2
	v_ashrrev_i32_e32 v4, 31, v56
	v_or_b32_e32 v4, 0x80000000, v4
	v_xor_b32_e32 v56, v4, v56
	v_cndmask_b32_e32 v56, 0, v56, vcc
	v_cmp_le_i32_e32 vcc, 0xcc0, v2
	v_ashrrev_i32_e32 v3, 31, v55
	v_or_b32_e32 v3, 0x80000000, v3
	v_xor_b32_e32 v55, v3, v55
	v_cndmask_b32_e32 v55, 0, v55, vcc
	v_cmp_le_i32_e32 vcc, 0xd00, v2
	v_ashrrev_i32_e32 v4, 31, v58
	v_or_b32_e32 v4, 0x80000000, v4
	v_xor_b32_e32 v58, v4, v58
	v_cndmask_b32_e32 v58, 0, v58, vcc
	v_cmp_le_i32_e32 vcc, 0xd40, v2
	v_ashrrev_i32_e32 v3, 31, v57
	v_or_b32_e32 v3, 0x80000000, v3
	v_xor_b32_e32 v57, v3, v57
	v_cndmask_b32_e32 v57, 0, v57, vcc
	v_cmp_le_i32_e32 vcc, 0xd80, v2
	v_ashrrev_i32_e32 v4, 31, v60
	v_or_b32_e32 v4, 0x80000000, v4
	v_xor_b32_e32 v60, v4, v60
	v_cndmask_b32_e32 v60, 0, v60, vcc
	v_cmp_le_i32_e32 vcc, 0xdc0, v2
	v_ashrrev_i32_e32 v3, 31, v59
	v_or_b32_e32 v3, 0x80000000, v3
	v_xor_b32_e32 v59, v3, v59
	v_cndmask_b32_e32 v59, 0, v59, vcc
	v_cmp_le_i32_e32 vcc, 0xe00, v2
	v_ashrrev_i32_e32 v4, 31, v62
	v_or_b32_e32 v4, 0x80000000, v4
	v_xor_b32_e32 v62, v4, v62
	v_cndmask_b32_e32 v62, 0, v62, vcc
	v_cmp_le_i32_e32 vcc, 0xe40, v2
	v_ashrrev_i32_e32 v3, 31, v61
	v_or_b32_e32 v3, 0x80000000, v3
	v_xor_b32_e32 v61, v3, v61
	v_cndmask_b32_e32 v61, 0, v61, vcc
	v_cmp_le_i32_e32 vcc, 0xe80, v2
	v_ashrrev_i32_e32 v4, 31, v64
	v_or_b32_e32 v4, 0x80000000, v4
	v_xor_b32_e32 v64, v4, v64
	v_cndmask_b32_e32 v64, 0, v64, vcc
	v_cmp_le_i32_e32 vcc, 0xec0, v2
	v_ashrrev_i32_e32 v3, 31, v63
	v_or_b32_e32 v3, 0x80000000, v3
	v_xor_b32_e32 v63, v3, v63
	v_cndmask_b32_e32 v63, 0, v63, vcc
	v_mov_b32_e32 v66, 0
	v_mov_b32_e32 v65, 0
	v_mov_b32_e32 v68, 0
	v_mov_b32_e32 v67, 0
.Ludsa_done:
	v_or_b32_e32 v0, 64, v163
	v_or_b32_e32 v2, 0x80, v163
	v_or_b32_e32 v3, 0xc0, v163
	v_or_b32_e32 v4, 0x100, v163
